# work stealing: other classes' counters read in one round trip instead of one failed draw per class
# baseline (speedup 1.0000x reference)
.Lqa_prompt:
	s_add_i32 s63, s26, -4
	s_and_b32 s64, s62, 1
	s_lshr_b32 s65, s62, 1
	s_mov_b32 s67, 0
	s_movk_i32 s66, 45
	s_sub_i32 s59, 64, s66
	s_cmp_eq_u32 s64, 0
	s_cselect_b32 s59, s59, s66
	s_cmp_lt_u32 s63, s59
	s_cbranch_scc1 .Lqa_found
	s_sub_i32 s63, s63, s59
	s_addk_i32 s67, 0x100
	s_movk_i32 s66, 37
	s_sub_i32 s59, 64, s66
	s_cmp_eq_u32 s64, 0
	s_cselect_b32 s59, s59, s66
	s_cmp_lt_u32 s63, s59
	s_cbranch_scc1 .Lqa_found
	s_sub_i32 s63, s63, s59
	s_addk_i32 s67, 0x100
	s_movk_i32 s66, 33
	s_sub_i32 s59, 64, s66
	s_cmp_eq_u32 s64, 0
	s_cselect_b32 s59, s59, s66
	s_cmp_lt_u32 s63, s59
	s_cbranch_scc1 .Lqa_found
	s_sub_i32 s63, s63, s59
	s_addk_i32 s67, 0x100
	s_movk_i32 s66, 32
	s_sub_i32 s59, 64, s66
	s_cmp_eq_u32 s64, 0
	s_cselect_b32 s59, s59, s66
	s_cmp_lt_u32 s63, s59
	s_cbranch_scc1 .Lqa_found
	s_sub_i32 s63, s63, s59
	s_addk_i32 s67, 0x100
	s_cmp_lt_u32 s63, 0x41
	s_cbranch_scc1 .Lqa_lru
	s_sub_i32 s63, s63, 0x41
	s_barrier
	v_cmp_gt_u32_e32 vcc, 7, v0
	s_and_saveexec_b64 s[0:1], vcc
	s_cbranch_execz .Lqa_nodraw
	v_add_u32_e32 v3, s98, v0
	v_add_u32_e32 v3, 1, v3
	v_add_u32_e32 v2, s80, v3
	v_and_b32_e32 v2, 7, v2
	v_lshlrev_b32_e32 v248, 6, v2
	s_add_u32 s8, s86, 0x1e28f900
	s_addc_u32 s9, s87, 0
	global_load_dword v249, v248, s[8:9] sc1
	v_and_b32_e32 v250, 1, v2
	v_cmp_eq_u32_e32 vcc, 1, v250
	v_mov_b32_e32 v251, 178
	v_mov_b32_e32 v250, 216
	v_cndmask_b32_e32 v251, v251, v250, vcc
	s_waitcnt vmcnt(0)
	v_cmp_lt_u32_e64 s[64:65], v249, v251
	v_cmp_gt_u32_e32 vcc, 8, v3
	s_and_b64 s[64:65], s[64:65], vcc
	s_and_b64 s[64:65], s[64:65], exec
	s_ff1_i32_b64 s66, s[64:65]
	s_cmp_lt_i32 s66, 0
	s_cbranch_scc1 .Lqa_none
	s_add_i32 s66, s66, s98
	s_add_i32 s66, s66, 1
	s_add_i32 s67, s80, s66
	s_and_b32 s67, s67, 7
	s_lshl_b32 s67, s67, 6
	s_add_u32 s8, s8, s67
	s_addc_u32 s9, s9, 0
	s_mov_b64 exec, 1
	v_mov_b32_e32 v2, 0
	v_mov_b32_e32 v3, 1
	s_nop 1
	global_atomic_add v3, v2, v3, s[8:9] sc0
	v_mov_b32_e32 v248, s66
	v_mov_b32_e32 v2, s3
	s_waitcnt vmcnt(0)
	ds_write2_b32 v2, v3, v248 offset1:1
	s_branch .Lqa_nodraw
.Lqa_none:
	s_mov_b64 exec, 1
	v_mov_b32_e32 v2, s3
	v_mov_b32_e32 v3, 0
	v_mov_b32_e32 v248, 8
	ds_write2_b32 v2, v3, v248 offset1:1
.Lqa_nodraw:
	s_or_b64 exec, exec, s[0:1]
	s_waitcnt lgkmcnt(0)
	s_barrier
	v_mov_b32_e32 v2, s3
	ds_read2_b32 v[2:3], v2 offset1:1
	s_waitcnt lgkmcnt(0)
	v_readfirstlane_b32 s26, v2
	v_readfirstlane_b32 s98, v3
	s_nop 3
	s_cmp_ge_u32 s98, 8
	s_cbranch_scc1 .LBB0_1418
	s_add_i32 s62, s80, s98
	s_and_b32 s62, s62, 7
	s_lshl_b32 s63, s62, 6
	s_add_u32 s8, s86, 0x1e28f900
	s_addc_u32 s9, s87, 0
	s_add_u32 s8, s8, s63
	s_addc_u32 s9, s9, 0
	s_branch .Lqa_top
